# Xr conversion items paired like the other transposing kinds; all 2048 RG-LRU summary units go through the P2 queue (none left for P3)
# speedup vs baseline: 1.0096x; 1.0096x over previous
.LBB0_672:
	s_or_b64 exec, exec, s[40:41]
	v_cndmask_b32_e64 v158, 0, 1.0, s[16:17]
	v_cndmask_b32_e64 v194, 0, 1.0, s[18:19]
	s_waitcnt vmcnt(23)
	v_lshlrev_b32_e32 v198, 16, v6
	v_and_b32_e32 v199, 0xffff0000, v6
	v_lshlrev_b32_e32 v6, 16, v7
	v_and_b32_e32 v7, 0xffff0000, v7
	s_waitcnt vmcnt(20)
	v_pk_mul_f32 v[128:129], v[158:159], v[128:129] op_sel_hi:[0,1]
	v_cndmask_b32_e64 v196, 0, 1.0, s[20:21]
	v_pk_mul_f32 v[126:127], v[158:159], v[126:127] op_sel_hi:[0,1]
	s_waitcnt vmcnt(17)
	v_lshlrev_b32_e32 v200, 16, v10
	v_and_b32_e32 v201, 0xffff0000, v10
	v_lshlrev_b32_e32 v10, 16, v11
	v_and_b32_e32 v11, 0xffff0000, v11
	s_waitcnt vmcnt(13)
	v_pk_mul_f32 v[132:133], v[194:195], v[132:133] op_sel_hi:[0,1]
	s_waitcnt vmcnt(0)
	v_add_u32_e32 v206, v252, v253
	v_mov_b32_e32 v207, 0x22048
	v_cmp_eq_u32_e64 s[50:51], 0, v0
	s_and_saveexec_b64 s[48:49], s[50:51]
	ds_write_b32 v207, v206
	s_or_b64 exec, exec, s[48:49]
	v_pk_fma_f32 v[6:7], v[128:129], v[6:7], v[144:145]
	v_pk_mul_f32 v[130:131], v[194:195], v[130:131] op_sel_hi:[0,1]
	v_lshlrev_b32_e32 v202, 16, v50
	v_and_b32_e32 v203, 0xffff0000, v50
	v_lshlrev_b32_e32 v50, 16, v51
	v_and_b32_e32 v51, 0xffff0000, v51
	v_pk_mul_f32 v[136:137], v[196:197], v[136:137] op_sel_hi:[0,1]
	v_pk_fma_f32 v[126:127], v[126:127], v[198:199], v[142:143]
	v_pk_fma_f32 v[6:7], v[132:133], v[10:11], v[6:7]
	v_pk_mul_f32 v[134:135], v[196:197], v[134:135] op_sel_hi:[0,1]
	v_lshlrev_b32_e32 v204, 16, v58
	v_and_b32_e32 v205, 0xffff0000, v58
	v_lshlrev_b32_e32 v58, 16, v59
	v_and_b32_e32 v59, 0xffff0000, v59
	v_pk_mul_f32 v[140:141], v[152:153], v[140:141]
	v_pk_fma_f32 v[10:11], v[130:131], v[200:201], v[126:127]
	v_pk_fma_f32 v[6:7], v[136:137], v[50:51], v[6:7]
	v_pk_mul_f32 v[138:139], v[150:151], v[138:139]
	v_pk_fma_f32 v[10:11], v[134:135], v[202:203], v[10:11]
	v_pk_fma_f32 v[128:129], v[140:141], v[58:59], v[6:7]
	v_lshlrev_b32_e32 v6, 16, v68
	v_and_b32_e32 v7, 0xffff0000, v68
	v_pk_mul_f32 v[58:59], v[158:159], v[106:107] op_sel_hi:[0,1]
	v_pk_fma_f32 v[126:127], v[138:139], v[204:205], v[10:11]
	v_lshlrev_b32_e32 v10, 16, v69
	v_and_b32_e32 v11, 0xffff0000, v69
	v_pk_mul_f32 v[50:51], v[158:159], v[108:109] op_sel_hi:[0,1]
	v_lshlrev_b32_e32 v68, 16, v76
	v_and_b32_e32 v69, 0xffff0000, v76
	v_pk_mul_f32 v[106:107], v[194:195], v[110:111] op_sel_hi:[0,1]
	v_pk_fma_f32 v[6:7], v[58:59], v[6:7], v[118:119]
	v_lshlrev_b32_e32 v76, 16, v77
	v_and_b32_e32 v77, 0xffff0000, v77
	v_pk_mul_f32 v[108:109], v[194:195], v[112:113] op_sel_hi:[0,1]
	v_lshlrev_b32_e32 v110, 16, v88
	v_and_b32_e32 v111, 0xffff0000, v88
	v_pk_mul_f32 v[114:115], v[196:197], v[114:115] op_sel_hi:[0,1]
	v_pk_fma_f32 v[10:11], v[50:51], v[10:11], v[120:121]
	v_pk_fma_f32 v[6:7], v[106:107], v[68:69], v[6:7]
	v_lshlrev_b32_e32 v88, 16, v89
	v_and_b32_e32 v89, 0xffff0000, v89
	v_pk_mul_f32 v[112:113], v[196:197], v[116:117] op_sel_hi:[0,1]
	v_lshlrev_b32_e32 v116, 16, v96
	v_and_b32_e32 v117, 0xffff0000, v96
	v_pk_mul_f32 v[122:123], v[150:151], v[122:123]
	v_pk_fma_f32 v[10:11], v[108:109], v[76:77], v[10:11]
	v_pk_fma_f32 v[6:7], v[114:115], v[110:111], v[6:7]
	v_lshlrev_b32_e32 v96, 16, v97
	v_and_b32_e32 v97, 0xffff0000, v97
	v_pk_mul_f32 v[124:125], v[152:153], v[124:125]
	v_pk_fma_f32 v[10:11], v[112:113], v[88:89], v[10:11]
	v_pk_fma_f32 v[106:107], v[122:123], v[116:117], v[6:7]
	v_lshlrev_b32_e32 v6, 16, v66
	v_and_b32_e32 v7, 0xffff0000, v66
	v_pk_mul_f32 v[58:59], v[158:159], v[70:71] op_sel_hi:[0,1]
	v_pk_fma_f32 v[108:109], v[124:125], v[96:97], v[10:11]
	v_lshlrev_b32_e32 v10, 16, v67
	v_and_b32_e32 v11, 0xffff0000, v67
	v_pk_mul_f32 v[50:51], v[158:159], v[72:73] op_sel_hi:[0,1]
	v_lshlrev_b32_e32 v66, 16, v74
	v_and_b32_e32 v67, 0xffff0000, v74
	v_pk_mul_f32 v[72:73], v[194:195], v[78:79] op_sel_hi:[0,1]
	v_pk_fma_f32 v[6:7], v[58:59], v[6:7], v[98:99]
	v_lshlrev_b32_e32 v68, 16, v75
	v_and_b32_e32 v69, 0xffff0000, v75
	v_pk_mul_f32 v[70:71], v[194:195], v[80:81] op_sel_hi:[0,1]
	v_lshlrev_b32_e32 v74, 16, v86
	v_and_b32_e32 v75, 0xffff0000, v86
	v_pk_mul_f32 v[80:81], v[196:197], v[90:91] op_sel_hi:[0,1]
	v_pk_fma_f32 v[10:11], v[50:51], v[10:11], v[100:101]
	v_pk_fma_f32 v[6:7], v[72:73], v[66:67], v[6:7]
	v_lshlrev_b32_e32 v76, 16, v87
	v_and_b32_e32 v77, 0xffff0000, v87
	v_pk_mul_f32 v[78:79], v[196:197], v[92:93] op_sel_hi:[0,1]
	v_lshlrev_b32_e32 v86, 16, v94
	v_and_b32_e32 v87, 0xffff0000, v94
	v_pk_mul_f32 v[92:93], v[150:151], v[102:103]
	v_pk_fma_f32 v[10:11], v[70:71], v[68:69], v[10:11]
	v_pk_fma_f32 v[6:7], v[80:81], v[74:75], v[6:7]
	v_lshlrev_b32_e32 v88, 16, v95
	v_and_b32_e32 v89, 0xffff0000, v95
	v_pk_mul_f32 v[90:91], v[152:153], v[104:105]
	v_pk_fma_f32 v[10:11], v[78:79], v[76:77], v[10:11]
	v_pk_fma_f32 v[66:67], v[92:93], v[86:87], v[6:7]
	v_lshlrev_b32_e32 v6, 16, v8
	v_and_b32_e32 v7, 0xffff0000, v8
	v_lshlrev_b32_e32 v8, 16, v9
	v_and_b32_e32 v9, 0xffff0000, v9
	v_pk_mul_f32 v[4:5], v[158:159], v[4:5] op_sel_hi:[0,1]
	v_pk_mul_f32 v[2:3], v[158:159], v[2:3] op_sel_hi:[0,1]
	v_pk_fma_f32 v[68:69], v[90:91], v[88:89], v[10:11]
	v_lshlrev_b32_e32 v10, 16, v12
	v_and_b32_e32 v11, 0xffff0000, v12
	v_lshlrev_b32_e32 v12, 16, v13
	v_and_b32_e32 v13, 0xffff0000, v13
	v_pk_mul_f32 v[22:23], v[194:195], v[22:23] op_sel_hi:[0,1]
	v_pk_mul_f32 v[24:25], v[194:195], v[24:25] op_sel_hi:[0,1]
	v_pk_fma_f32 v[2:3], v[2:3], v[6:7], v[82:83]
	v_pk_fma_f32 v[4:5], v[4:5], v[8:9], v[84:85]
	v_lshlrev_b32_e32 v50, 16, v52
	v_and_b32_e32 v51, 0xffff0000, v52
	v_lshlrev_b32_e32 v52, 16, v53
	v_and_b32_e32 v53, 0xffff0000, v53
	v_pk_mul_f32 v[56:57], v[196:197], v[56:57] op_sel_hi:[0,1]
	v_pk_mul_f32 v[54:55], v[196:197], v[54:55] op_sel_hi:[0,1]
	v_pk_fma_f32 v[4:5], v[24:25], v[12:13], v[4:5]
	v_pk_fma_f32 v[2:3], v[22:23], v[10:11], v[2:3]
	v_lshlrev_b32_e32 v58, 16, v60
	v_and_b32_e32 v59, 0xffff0000, v60
	v_lshlrev_b32_e32 v60, 16, v61
	v_and_b32_e32 v61, 0xffff0000, v61
	v_pk_mul_f32 v[64:65], v[152:153], v[64:65]
	v_pk_mul_f32 v[62:63], v[150:151], v[62:63]
	v_pk_fma_f32 v[2:3], v[54:55], v[50:51], v[2:3]
	v_pk_fma_f32 v[4:5], v[56:57], v[52:53], v[4:5]
	v_pk_fma_f32 v[2:3], v[62:63], v[58:59], v[2:3]
	v_pk_fma_f32 v[4:5], v[64:65], v[60:61], v[4:5]
	ds_write_b128 v167, v[66:69]
	ds_write_b128 v167, v[106:109] offset:16
	ds_write_b128 v167, v[126:129] offset:32
	ds_write_b128 v167, v[2:5] offset:48
	v_cvt_pk_bf16_f32 v6, v66, v67
	v_cvt_pk_bf16_f32 v7, v68, v69
	v_cvt_pk_bf16_f32 v8, v106, v107
	v_cvt_pk_bf16_f32 v9, v108, v109
	v_cvt_pk_bf16_f32 v10, v126, v127
	v_cvt_pk_bf16_f32 v11, v128, v129
	v_cvt_pk_bf16_f32 v12, v2, v3
	v_cvt_pk_bf16_f32 v13, v4, v5
	ds_write_b128 v168, v[6:9] offset:33792
	ds_write_b128 v168, v[10:13] offset:33808
	s_waitcnt lgkmcnt(0)
	s_barrier
	v_mov_b32_e32 v207, 0x22048
	ds_read_b32 v206, v207
	v_lshrrev_b32_e32 v208, 3, v0
	v_and_b32_e32 v209, 7, v0
	v_lshlrev_b32_e32 v209, 5, v209
	s_waitcnt lgkmcnt(0)
	v_readfirstlane_b32 s47, v206
	s_nop 0
	s_cmp_lt_u32 s47, 0x800
	s_cbranch_scc0 .Llpf_skip
	s_bfe_u32 s48, s47, 0x60004
	s_lshl_b32 s48, s48, 6
	s_lshr_b32 s49, s47, 10
	s_lshl_b32 s49, s49, 12
	s_or_b32 s48, s48, s49
	s_and_b32 s49, s47, 15
	s_lshl_b32 s49, s49, 8
	v_add_u32_e32 v208, s48, v208
	v_lshlrev_b32_e32 v208, 12, v208
	v_add3_u32 v208, v208, v209, s49
	global_load_dwordx4 v[212:215], v208, s[26:27]
	global_load_dwordx4 v[216:219], v208, s[26:27] offset:16
